# P2(a): hand-written wave-uniform short-conv loop (all loads of an item issued together, weights loaded once) on top of the de-serialised LayerNorm passes
# baseline (speedup 1.0000x reference)
.LBB0_327:
	s_or_b64 exec, exec, s[4:5]
	v_mov_b32_e32 v126, v164
	s_waitcnt lgkmcnt(0)
	s_barrier
	s_and_b32 s98, s2, 7
	s_lshl_b32 s98, s98, 5
	s_lshr_b32 s99, s2, 3
	s_add_i32 s98, s98, s99
	s_cmpk_lg_i32 s26, 0x100
	s_cselect_b32 s98, s2, s98
	s_add_u32 s14, s34, 0xc000000
	v_lshrrev_b32_e32 v154, 7, v126
	v_mul_u32_u24_e32 v154, s26, v154
	v_add_u32_e32 v154, s98, v154
	v_and_b32_e32 v155, 0x7f, v126
	v_lshl_add_u32 v94, v154, 7, v155
	s_mov_b32 s3, 0x48000
	s_addc_u32 s15, s35, 0
	s_mov_b32 s6, 12
	s_mov_b32 s4, 2
	v_cmp_gt_i32_e32 vcc, s3, v94
	v_lshlrev_b32_e32 v127, 3, v126
	s_and_saveexec_b64 s[8:9], vcc
	s_cbranch_execz .LBB0_340
	s_ashr_i32 s7, s6, 31
	s_lshl_b64 s[6:7], s[6:7], 3
	s_add_u32 s6, s0, s6
	s_addc_u32 s7, s1, s7
	s_ashr_i32 s5, s4, 31
	s_lshl_b64 s[4:5], s[4:5], 3
	s_add_u32 s4, s0, s4
	s_addc_u32 s5, s1, s5
	s_load_dwordx2 s[10:11], s[6:7], 0x0
	s_load_dwordx2 s[38:39], s[4:5], 0x0
	s_lshl_b32 s3, s26, 9
	v_lshlrev_b32_e32 v95, 3, v94
	s_lshl_b32 s19, s26, 12
	s_mov_b64 s[40:41], 0
	s_movk_i32 s25, 0x1fff
	s_movk_i32 s29, 0x2000
	v_mov_b32_e32 v96, 0x7fc
	v_mov_b32_e32 v49, 0
	s_movk_i32 s48, 0x4800
	s_movk_i32 s49, 0x1000
	s_mov_b64 s[42:43], 0x1000
	s_mov_b64 s[44:45], 0x2000
	s_mov_b32 s50, 0x17200000
	s_mov_b32 s51, 0x47fff
	v_mov_b32_e32 v97, 0x5808000
	v_mov_b32_e32 v98, 0x5800000
	s_cmpk_lg_i32 s26, 0x100
	s_cbranch_scc1 .LBB0_330
	s_waitcnt lgkmcnt(0)
	v_and_b32_e32 v154, 0x7f, v94
	v_lshlrev_b32_e32 v157, 5, v154
	v_lshlrev_b32_e32 v154, 4, v154
	v_add_u32_e32 v155, 0x1000, v154
	v_add_u32_e32 v156, 0x2000, v154
	v_add_u32_e32 v158, 0x1000, v157
	v_add_u32_e32 v159, 0x2000, v157
	global_load_dwordx4 v[0:3], v157, s[10:11]
	global_load_dwordx4 v[4:7], v157, s[10:11] offset:16
	global_load_dwordx4 v[8:11], v158, s[10:11]
	global_load_dwordx4 v[12:15], v158, s[10:11] offset:16
	global_load_dwordx4 v[16:19], v159, s[10:11]
	global_load_dwordx4 v[20:23], v159, s[10:11] offset:16
	v_lshrrev_b32_e32 v88, 7, v94
	s_lshr_b32 s4, s77, 1
	s_lshl_b32 s4, s4, 8
	s_add_i32 s4, s4, s98
.Lcv_loop:
	s_lshl_b32 s52, s4, 2
	s_cmpk_lt_u32 s52, 0x2000
	s_cselect_b32 s99, 1, 0
	s_sub_i32 s5, s52, 0x2000
	s_and_b32 s53, s5, 7
	s_lshr_b32 s98, s5, 3
	s_cmp_eq_u32 s99, 1
	s_cbranch_scc0 .Lcv_ps
	s_and_b32 s53, s52, 0x7ff
	s_lshr_b32 s98, s52, 11
.Lcv_ps:
	s_mul_i32 s5, s52, 0x4800
	s_add_u32 s6, s14, s5
	s_addc_u32 s7, s15, 0
	s_mov_b32 s101, 0
	s_cmp_eq_u32 s53, 0
	s_cbranch_scc1 .Lcv_h0
	s_sub_u32 s46, s6, 0x9000
	s_subb_u32 s47, s7, 0
	global_load_dwordx4 v[24:27], v155, s[46:47] offset:2048
	global_load_dwordx4 v[28:31], v156, s[46:47]
	s_add_u32 s46, s46, 0x4800
	s_addc_u32 s47, s47, 0
	global_load_dwordx4 v[32:35], v155, s[46:47] offset:2048
	global_load_dwordx4 v[36:39], v156, s[46:47]
	s_mov_b32 s101, 1
	s_branch .Lcv_hd
.Lcv_h0:
	s_cmp_eq_u32 s99, 1
	s_cbranch_scc1 .Lcv_hz
	s_lshl_b32 s5, s98, 13
	s_add_u32 s46, s38, s5
	s_addc_u32 s47, s39, 0
	global_load_dwordx4 v[100:103], v157, s[46:47]
	global_load_dwordx4 v[104:107], v157, s[46:47] offset:16
	global_load_dwordx4 v[108:111], v158, s[46:47]
	global_load_dwordx4 v[112:115], v158, s[46:47] offset:16
	s_branch .Lcv_hd
.Lcv_hz:
	v_mov_b32_e32 v100, 0
	v_mov_b32_e32 v108, 0
	v_mov_b32_e32 v101, 0
	v_mov_b32_e32 v109, 0
	v_mov_b32_e32 v102, 0
	v_mov_b32_e32 v110, 0
	v_mov_b32_e32 v103, 0
	v_mov_b32_e32 v111, 0
	v_mov_b32_e32 v104, 0
	v_mov_b32_e32 v112, 0
	v_mov_b32_e32 v105, 0
	v_mov_b32_e32 v113, 0
	v_mov_b32_e32 v106, 0
	v_mov_b32_e32 v114, 0
	v_mov_b32_e32 v107, 0
	v_mov_b32_e32 v115, 0
.Lcv_hd:
	global_load_dwordx4 v[40:43], v155, s[6:7] offset:2048
	global_load_dwordx4 v[44:47], v156, s[6:7]
	global_load_dwordx4 v[48:51], v155, s[6:7]
	s_add_u32 s6, s6, 0x4800
	s_addc_u32 s7, s7, 0
	global_load_dwordx4 v[52:55], v155, s[6:7] offset:2048
	global_load_dwordx4 v[56:59], v156, s[6:7]
	global_load_dwordx4 v[60:63], v155, s[6:7]
	s_add_u32 s6, s6, 0x4800
	s_addc_u32 s7, s7, 0
	global_load_dwordx4 v[64:67], v155, s[6:7] offset:2048
	global_load_dwordx4 v[68:71], v156, s[6:7]
	global_load_dwordx4 v[72:75], v155, s[6:7]
	s_add_u32 s6, s6, 0x4800
	s_addc_u32 s7, s7, 0
	global_load_dwordx4 v[76:79], v155, s[6:7] offset:2048
	global_load_dwordx4 v[80:83], v156, s[6:7]
	global_load_dwordx4 v[84:87], v155, s[6:7]
	s_lshl_b32 s5, s52, 12
	s_add_u32 s40, s34, s5
	s_addc_u32 s41, s35, 0
	s_add_u32 s40, s40, 0x17200800
	s_addc_u32 s41, s41, 0
	s_waitcnt vmcnt(0)
	s_cmp_eq_u32 s101, 1
	s_cbranch_scc0 .Lcv_nh
	v_lshlrev_b32_e32 v88, 16, v24
	v_lshlrev_b32_e32 v89, 16, v28
	v_mul_f32_e32 v100, v88, v89
	v_and_b32_e32 v90, 0xffff0000, v24
	v_and_b32_e32 v91, 0xffff0000, v28
	v_mul_f32_e32 v101, v90, v91
	v_lshlrev_b32_e32 v88, 16, v25
	v_lshlrev_b32_e32 v89, 16, v29
	v_mul_f32_e32 v102, v88, v89
	v_and_b32_e32 v90, 0xffff0000, v25
	v_and_b32_e32 v91, 0xffff0000, v29
	v_mul_f32_e32 v103, v90, v91
	v_lshlrev_b32_e32 v88, 16, v26
	v_lshlrev_b32_e32 v89, 16, v30
	v_mul_f32_e32 v104, v88, v89
	v_and_b32_e32 v90, 0xffff0000, v26
	v_and_b32_e32 v91, 0xffff0000, v30
	v_mul_f32_e32 v105, v90, v91
	v_lshlrev_b32_e32 v88, 16, v27
	v_lshlrev_b32_e32 v89, 16, v31
	v_mul_f32_e32 v106, v88, v89
	v_and_b32_e32 v90, 0xffff0000, v27
	v_and_b32_e32 v91, 0xffff0000, v31
	v_mul_f32_e32 v107, v90, v91
	v_lshlrev_b32_e32 v88, 16, v32
	v_lshlrev_b32_e32 v89, 16, v36
	v_mul_f32_e32 v108, v88, v89
	v_and_b32_e32 v90, 0xffff0000, v32
	v_and_b32_e32 v91, 0xffff0000, v36
	v_mul_f32_e32 v109, v90, v91
	v_lshlrev_b32_e32 v88, 16, v33
	v_lshlrev_b32_e32 v89, 16, v37
	v_mul_f32_e32 v110, v88, v89
	v_and_b32_e32 v90, 0xffff0000, v33
	v_and_b32_e32 v91, 0xffff0000, v37
	v_mul_f32_e32 v111, v90, v91
	v_lshlrev_b32_e32 v88, 16, v34
	v_lshlrev_b32_e32 v89, 16, v38
	v_mul_f32_e32 v112, v88, v89
	v_and_b32_e32 v90, 0xffff0000, v34
	v_and_b32_e32 v91, 0xffff0000, v38
	v_mul_f32_e32 v113, v90, v91
	v_lshlrev_b32_e32 v88, 16, v35
	v_lshlrev_b32_e32 v89, 16, v39
	v_mul_f32_e32 v114, v88, v89
	v_and_b32_e32 v90, 0xffff0000, v35
	v_and_b32_e32 v91, 0xffff0000, v39
	v_mul_f32_e32 v115, v90, v91
.Lcv_nh:
	v_lshlrev_b32_e32 v88, 16, v40
	v_lshlrev_b32_e32 v89, 16, v44
	v_mul_f32_e32 v116, v88, v89
	v_and_b32_e32 v90, 0xffff0000, v40
	v_and_b32_e32 v91, 0xffff0000, v44
	v_mul_f32_e32 v117, v90, v91
	v_lshlrev_b32_e32 v88, 16, v41
	v_lshlrev_b32_e32 v89, 16, v45
	v_mul_f32_e32 v118, v88, v89
	v_and_b32_e32 v90, 0xffff0000, v41
	v_and_b32_e32 v91, 0xffff0000, v45
	v_mul_f32_e32 v119, v90, v91
	v_lshlrev_b32_e32 v88, 16, v42
	v_lshlrev_b32_e32 v89, 16, v46
	v_mul_f32_e32 v120, v88, v89
	v_and_b32_e32 v90, 0xffff0000, v42
	v_and_b32_e32 v91, 0xffff0000, v46
	v_mul_f32_e32 v121, v90, v91
	v_lshlrev_b32_e32 v88, 16, v43
	v_lshlrev_b32_e32 v89, 16, v47
	v_mul_f32_e32 v122, v88, v89
	v_and_b32_e32 v90, 0xffff0000, v43
	v_and_b32_e32 v91, 0xffff0000, v47
	v_mul_f32_e32 v123, v90, v91
	v_lshlrev_b32_e32 v88, 16, v52
	v_lshlrev_b32_e32 v89, 16, v56
	v_mul_f32_e32 v128, v88, v89
	v_and_b32_e32 v90, 0xffff0000, v52
	v_and_b32_e32 v91, 0xffff0000, v56
	v_mul_f32_e32 v129, v90, v91
	v_lshlrev_b32_e32 v88, 16, v53
	v_lshlrev_b32_e32 v89, 16, v57
	v_mul_f32_e32 v130, v88, v89
	v_and_b32_e32 v90, 0xffff0000, v53
	v_and_b32_e32 v91, 0xffff0000, v57
	v_mul_f32_e32 v131, v90, v91
	v_lshlrev_b32_e32 v88, 16, v54
	v_lshlrev_b32_e32 v89, 16, v58
	v_mul_f32_e32 v132, v88, v89
	v_and_b32_e32 v90, 0xffff0000, v54
	v_and_b32_e32 v91, 0xffff0000, v58
	v_mul_f32_e32 v133, v90, v91
	v_lshlrev_b32_e32 v88, 16, v55
	v_lshlrev_b32_e32 v89, 16, v59
	v_mul_f32_e32 v134, v88, v89
	v_and_b32_e32 v90, 0xffff0000, v55
	v_and_b32_e32 v91, 0xffff0000, v59
	v_mul_f32_e32 v135, v90, v91
	v_lshlrev_b32_e32 v88, 16, v64
	v_lshlrev_b32_e32 v89, 16, v68
	v_mul_f32_e32 v136, v88, v89
	v_and_b32_e32 v90, 0xffff0000, v64
	v_and_b32_e32 v91, 0xffff0000, v68
	v_mul_f32_e32 v137, v90, v91
	v_lshlrev_b32_e32 v88, 16, v65
	v_lshlrev_b32_e32 v89, 16, v69
	v_mul_f32_e32 v138, v88, v89
	v_and_b32_e32 v90, 0xffff0000, v65
	v_and_b32_e32 v91, 0xffff0000, v69
	v_mul_f32_e32 v139, v90, v91
	v_lshlrev_b32_e32 v88, 16, v66
	v_lshlrev_b32_e32 v89, 16, v70
	v_mul_f32_e32 v140, v88, v89
	v_and_b32_e32 v90, 0xffff0000, v66
	v_and_b32_e32 v91, 0xffff0000, v70
	v_mul_f32_e32 v141, v90, v91
	v_lshlrev_b32_e32 v88, 16, v67
	v_lshlrev_b32_e32 v89, 16, v71
	v_mul_f32_e32 v142, v88, v89
	v_and_b32_e32 v90, 0xffff0000, v67
	v_and_b32_e32 v91, 0xffff0000, v71
	v_mul_f32_e32 v143, v90, v91
	v_lshlrev_b32_e32 v88, 16, v76
	v_lshlrev_b32_e32 v89, 16, v80
	v_mul_f32_e32 v144, v88, v89
	v_and_b32_e32 v90, 0xffff0000, v76
	v_and_b32_e32 v91, 0xffff0000, v80
	v_mul_f32_e32 v145, v90, v91
	v_lshlrev_b32_e32 v88, 16, v77
	v_lshlrev_b32_e32 v89, 16, v81
	v_mul_f32_e32 v146, v88, v89
	v_and_b32_e32 v90, 0xffff0000, v77
	v_and_b32_e32 v91, 0xffff0000, v81
	v_mul_f32_e32 v147, v90, v91
	v_lshlrev_b32_e32 v88, 16, v78
	v_lshlrev_b32_e32 v89, 16, v82
	v_mul_f32_e32 v148, v88, v89
	v_and_b32_e32 v90, 0xffff0000, v78
	v_and_b32_e32 v91, 0xffff0000, v82
	v_mul_f32_e32 v149, v90, v91
	v_lshlrev_b32_e32 v88, 16, v79
	v_lshlrev_b32_e32 v89, 16, v83
	v_mul_f32_e32 v150, v88, v89
	v_and_b32_e32 v90, 0xffff0000, v79
	v_and_b32_e32 v91, 0xffff0000, v83
	v_mul_f32_e32 v151, v90, v91
	v_mul_f32_e32 v88, v0, v100
	v_fmac_f32_e32 v88, v8, v108
	v_fmac_f32_e32 v88, v16, v116
	v_lshlrev_b32_e32 v90, 16, v48
	v_mul_f32_e32 v88, v90, v88
	v_mul_f32_e32 v89, v1, v101
	v_fmac_f32_e32 v89, v9, v109
	v_fmac_f32_e32 v89, v17, v117
	v_and_b32_e32 v90, 0xffff0000, v48
	v_mul_f32_e32 v89, v90, v89
	v_cvt_pk_bf16_f32 v48, v88, v89
	v_mul_f32_e32 v88, v2, v102
	v_fmac_f32_e32 v88, v10, v110
	v_fmac_f32_e32 v88, v18, v118
	v_lshlrev_b32_e32 v90, 16, v49
	v_mul_f32_e32 v88, v90, v88
	v_mul_f32_e32 v89, v3, v103
	v_fmac_f32_e32 v89, v11, v111
	v_fmac_f32_e32 v89, v19, v119
	v_and_b32_e32 v90, 0xffff0000, v49
	v_mul_f32_e32 v89, v90, v89
	v_cvt_pk_bf16_f32 v49, v88, v89
	v_mul_f32_e32 v88, v4, v104
	v_fmac_f32_e32 v88, v12, v112
	v_fmac_f32_e32 v88, v20, v120
	v_lshlrev_b32_e32 v90, 16, v50
	v_mul_f32_e32 v88, v90, v88
	v_mul_f32_e32 v89, v5, v105
	v_fmac_f32_e32 v89, v13, v113
	v_fmac_f32_e32 v89, v21, v121
	v_and_b32_e32 v90, 0xffff0000, v50
	v_mul_f32_e32 v89, v90, v89
	v_cvt_pk_bf16_f32 v50, v88, v89
	v_mul_f32_e32 v88, v6, v106
	v_fmac_f32_e32 v88, v14, v114
	v_fmac_f32_e32 v88, v22, v122
	v_lshlrev_b32_e32 v90, 16, v51
	v_mul_f32_e32 v88, v90, v88
	v_mul_f32_e32 v89, v7, v107
	v_fmac_f32_e32 v89, v15, v115
	v_fmac_f32_e32 v89, v23, v123
	v_and_b32_e32 v90, 0xffff0000, v51
	v_mul_f32_e32 v89, v90, v89
	v_cvt_pk_bf16_f32 v51, v88, v89
	global_store_dwordx4 v154, v[48:51], s[40:41]
	s_add_u32 s40, s40, 0x1000
	s_addc_u32 s41, s41, 0
	v_mul_f32_e32 v88, v0, v108
	v_fmac_f32_e32 v88, v8, v116
	v_fmac_f32_e32 v88, v16, v128
	v_lshlrev_b32_e32 v90, 16, v60
	v_mul_f32_e32 v88, v90, v88
	v_mul_f32_e32 v89, v1, v109
	v_fmac_f32_e32 v89, v9, v117
	v_fmac_f32_e32 v89, v17, v129
	v_and_b32_e32 v90, 0xffff0000, v60
	v_mul_f32_e32 v89, v90, v89
	v_cvt_pk_bf16_f32 v60, v88, v89
	v_mul_f32_e32 v88, v2, v110
	v_fmac_f32_e32 v88, v10, v118
	v_fmac_f32_e32 v88, v18, v130
	v_lshlrev_b32_e32 v90, 16, v61
	v_mul_f32_e32 v88, v90, v88
	v_mul_f32_e32 v89, v3, v111
	v_fmac_f32_e32 v89, v11, v119
	v_fmac_f32_e32 v89, v19, v131
	v_and_b32_e32 v90, 0xffff0000, v61
	v_mul_f32_e32 v89, v90, v89
	v_cvt_pk_bf16_f32 v61, v88, v89
	v_mul_f32_e32 v88, v4, v112
	v_fmac_f32_e32 v88, v12, v120
	v_fmac_f32_e32 v88, v20, v132
	v_lshlrev_b32_e32 v90, 16, v62
	v_mul_f32_e32 v88, v90, v88
	v_mul_f32_e32 v89, v5, v113
	v_fmac_f32_e32 v89, v13, v121
	v_fmac_f32_e32 v89, v21, v133
	v_and_b32_e32 v90, 0xffff0000, v62
	v_mul_f32_e32 v89, v90, v89
	v_cvt_pk_bf16_f32 v62, v88, v89
	v_mul_f32_e32 v88, v6, v114
	v_fmac_f32_e32 v88, v14, v122
	v_fmac_f32_e32 v88, v22, v134
	v_lshlrev_b32_e32 v90, 16, v63
	v_mul_f32_e32 v88, v90, v88
	v_mul_f32_e32 v89, v7, v115
	v_fmac_f32_e32 v89, v15, v123
	v_fmac_f32_e32 v89, v23, v135
	v_and_b32_e32 v90, 0xffff0000, v63
	v_mul_f32_e32 v89, v90, v89
	v_cvt_pk_bf16_f32 v63, v88, v89
	global_store_dwordx4 v154, v[60:63], s[40:41]
	s_add_u32 s40, s40, 0x1000
	s_addc_u32 s41, s41, 0
	v_mul_f32_e32 v88, v0, v116
	v_fmac_f32_e32 v88, v8, v128
	v_fmac_f32_e32 v88, v16, v136
	v_lshlrev_b32_e32 v90, 16, v72
	v_mul_f32_e32 v88, v90, v88
	v_mul_f32_e32 v89, v1, v117
	v_fmac_f32_e32 v89, v9, v129
	v_fmac_f32_e32 v89, v17, v137
	v_and_b32_e32 v90, 0xffff0000, v72
	v_mul_f32_e32 v89, v90, v89
	v_cvt_pk_bf16_f32 v72, v88, v89
	v_mul_f32_e32 v88, v2, v118
	v_fmac_f32_e32 v88, v10, v130
	v_fmac_f32_e32 v88, v18, v138
	v_lshlrev_b32_e32 v90, 16, v73
	v_mul_f32_e32 v88, v90, v88
	v_mul_f32_e32 v89, v3, v119
	v_fmac_f32_e32 v89, v11, v131
	v_fmac_f32_e32 v89, v19, v139
	v_and_b32_e32 v90, 0xffff0000, v73
	v_mul_f32_e32 v89, v90, v89
	v_cvt_pk_bf16_f32 v73, v88, v89
	v_mul_f32_e32 v88, v4, v120
	v_fmac_f32_e32 v88, v12, v132
	v_fmac_f32_e32 v88, v20, v140
	v_lshlrev_b32_e32 v90, 16, v74
	v_mul_f32_e32 v88, v90, v88
	v_mul_f32_e32 v89, v5, v121
	v_fmac_f32_e32 v89, v13, v133
	v_fmac_f32_e32 v89, v21, v141
	v_and_b32_e32 v90, 0xffff0000, v74
	v_mul_f32_e32 v89, v90, v89
	v_cvt_pk_bf16_f32 v74, v88, v89
	v_mul_f32_e32 v88, v6, v122
	v_fmac_f32_e32 v88, v14, v134
	v_fmac_f32_e32 v88, v22, v142
	v_lshlrev_b32_e32 v90, 16, v75
	v_mul_f32_e32 v88, v90, v88
	v_mul_f32_e32 v89, v7, v123
	v_fmac_f32_e32 v89, v15, v135
	v_fmac_f32_e32 v89, v23, v143
	v_and_b32_e32 v90, 0xffff0000, v75
	v_mul_f32_e32 v89, v90, v89
	v_cvt_pk_bf16_f32 v75, v88, v89
	global_store_dwordx4 v154, v[72:75], s[40:41]
	s_add_u32 s40, s40, 0x1000
	s_addc_u32 s41, s41, 0
	v_mul_f32_e32 v88, v0, v128
	v_fmac_f32_e32 v88, v8, v136
	v_fmac_f32_e32 v88, v16, v144
	v_lshlrev_b32_e32 v90, 16, v84
	v_mul_f32_e32 v88, v90, v88
	v_mul_f32_e32 v89, v1, v129
	v_fmac_f32_e32 v89, v9, v137
	v_fmac_f32_e32 v89, v17, v145
	v_and_b32_e32 v90, 0xffff0000, v84
	v_mul_f32_e32 v89, v90, v89
	v_cvt_pk_bf16_f32 v84, v88, v89
	v_mul_f32_e32 v88, v2, v130
	v_fmac_f32_e32 v88, v10, v138
	v_fmac_f32_e32 v88, v18, v146
	v_lshlrev_b32_e32 v90, 16, v85
	v_mul_f32_e32 v88, v90, v88
	v_mul_f32_e32 v89, v3, v131
	v_fmac_f32_e32 v89, v11, v139
	v_fmac_f32_e32 v89, v19, v147
	v_and_b32_e32 v90, 0xffff0000, v85
	v_mul_f32_e32 v89, v90, v89
	v_cvt_pk_bf16_f32 v85, v88, v89
	v_mul_f32_e32 v88, v4, v132
	v_fmac_f32_e32 v88, v12, v140
	v_fmac_f32_e32 v88, v20, v148
	v_lshlrev_b32_e32 v90, 16, v86
	v_mul_f32_e32 v88, v90, v88
	v_mul_f32_e32 v89, v5, v133
	v_fmac_f32_e32 v89, v13, v141
	v_fmac_f32_e32 v89, v21, v149
	v_and_b32_e32 v90, 0xffff0000, v86
	v_mul_f32_e32 v89, v90, v89
	v_cvt_pk_bf16_f32 v86, v88, v89
	v_mul_f32_e32 v88, v6, v134
	v_fmac_f32_e32 v88, v14, v142
	v_fmac_f32_e32 v88, v22, v150
	v_lshlrev_b32_e32 v90, 16, v87
	v_mul_f32_e32 v88, v90, v88
	v_mul_f32_e32 v89, v7, v135
	v_fmac_f32_e32 v89, v15, v143
	v_fmac_f32_e32 v89, v23, v151
	v_and_b32_e32 v90, 0xffff0000, v87
	v_mul_f32_e32 v89, v90, v89
	v_cvt_pk_bf16_f32 v87, v88, v89
	global_store_dwordx4 v154, v[84:87], s[40:41]
	s_cmp_eq_u32 s99, 1
	s_cselect_b32 s5, 0x7fc, 4
	s_cmp_eq_u32 s53, s5
	s_cbranch_scc0 .Lcv_nst
	s_mov_b32 s5, 0x5808000
	s_cmp_eq_u32 s99, 1
	s_cselect_b32 s5, 0x5800000, s5
	s_add_u32 s46, s20, s5
	s_addc_u32 s47, s21, 0
	s_lshl_b32 s5, s98, 13
	s_add_u32 s46, s46, s5
	s_addc_u32 s47, s47, 0
	global_store_dwordx4 v157, v[136:139], s[46:47]
	global_store_dwordx4 v157, v[140:143], s[46:47] offset:16
	global_store_dwordx4 v158, v[144:147], s[46:47]
	global_store_dwordx4 v158, v[148:151], s[46:47] offset:16
	s_nop 1
.Lcv_nst:
	s_addk_i32 s4, 0x400
	s_cmpk_lt_u32 s4, 0x900
	s_cbranch_scc1 .Lcv_loop
	s_branch .LBB0_340
	s_branch .LBB0_330
